# MLA QK: pipelined K-fragment reads with 6 rotating buffers (multi-consumer), stale nops removed
# baseline (speedup 1.0000x reference)
.LBB0_291:
	s_add_i32 s5, s1, -1
	s_min_i32 s6, s5, s4
	s_lshl_b32 s7, s6, 6
	s_add_i32 s7, s7, s16
	v_add_u32_e32 v52, s7, v205
	v_add_u32_e32 v44, s7, v203
	v_add_u32_e32 v48, s7, v204
	v_ashrrev_i32_e32 v53, 31, v52
	v_ashrrev_i32_e32 v45, 31, v44
	s_movk_i32 s18, 0xff80
	v_ashrrev_i32_e32 v49, 31, v48
	v_lshlrev_b64 v[54:55], 9, v[52:53]
	v_lshlrev_b64 v[52:53], 6, v[52:53]
	v_lshlrev_b64 v[46:47], 9, v[44:45]
	v_lshlrev_b64 v[44:45], 6, v[44:45]
	s_mov_b32 s19, -1
	v_lshlrev_b64 v[50:51], 9, v[48:49]
	v_lshlrev_b64 v[48:49], 6, v[48:49]
	v_lshl_add_u64 v[52:53], v[160:161], 0, v[52:53]
	v_lshl_add_u64 v[44:45], v[152:153], 0, v[44:45]
	v_lshl_add_u64 v[48:49], v[156:157], 0, v[48:49]
	v_lshl_add_u64 v[54:55], v[162:163], 0, v[54:55]
	v_lshl_add_u64 v[52:53], v[52:53], 0, s[18:19]
	v_lshl_add_u64 v[46:47], v[154:155], 0, v[46:47]
	v_lshl_add_u64 v[44:45], v[44:45], 0, s[18:19]
	v_lshl_add_u64 v[50:51], v[158:159], 0, v[50:51]
	v_lshl_add_u64 v[48:49], v[48:49], 0, s[18:19]
	v_cndmask_b32_e64 v53, v53, v55, s[42:43]
	v_cndmask_b32_e64 v52, v52, v54, s[42:43]
	s_lshl_b32 s94, s6, 7
	v_cndmask_b32_e64 v45, v45, v47, s[38:39]
	v_cndmask_b32_e64 v44, v44, v46, s[38:39]
	v_cndmask_b32_e64 v49, v49, v51, s[40:41]
	v_cndmask_b32_e64 v48, v48, v50, s[40:41]
	global_load_dwordx4 v[56:59], v[52:53], off
	v_lshl_add_u64 v[52:53], v[146:147], 0, s[94:95]
	v_lshl_add_u64 v[54:55], v[148:149], 0, s[94:95]
	global_load_dwordx4 v[44:47], v[44:45], off
	s_nop 0
	global_load_dwordx4 v[48:51], v[48:49], off
	s_nop 0
	global_load_dwordx4 v[60:63], v[52:53], off
	s_nop 0
	global_load_dwordx4 v[52:55], v[54:55], off
	s_setprio 1
	ds_read_b128 v[216:219], v151
	ds_read_b128 v[220:223], v151 offset:64
	ds_read_b128 v[224:227], v151 offset:128
	ds_read_b128 v[228:231], v151 offset:3328
	ds_read_b128 v[248:251], v151 offset:3392
	ds_read_b128 v[252:255], v151 offset:3456
	v_xor_b32_e32 v96, 0x80000000, v165
	v_pk_add_f32 v[100:101], v[164:165], 0 neg_lo:[1,1] neg_hi:[1,1]
	v_mov_b32_e32 v97, v96
	v_mov_b32_e32 v98, v96
	v_mov_b32_e32 v99, v96
	v_mov_b32_e32 v101, v100
	v_mov_b32_e32 v102, v100
	v_mov_b32_e32 v103, v100
	s_waitcnt lgkmcnt(5)
	v_mfma_f32_16x16x32_bf16 v[108:111], v[216:219], v[8:11], v[96:99]
	v_mfma_f32_16x16x32_bf16 v[104:107], v[216:219], v[20:23], v[100:103]
	ds_read_b128 v[216:219], v151 offset:6656
	s_waitcnt lgkmcnt(5)
	v_mfma_f32_16x16x32_bf16 v[108:111], v[220:223], v[12:15], v[108:111]
	v_mfma_f32_16x16x32_bf16 v[104:107], v[220:223], v[24:27], v[104:107]
	ds_read_b128 v[220:223], v151 offset:6720
	s_waitcnt lgkmcnt(5)
	v_mfma_f32_16x16x32_bf16 v[116:119], v[224:227], v[16:19], v[108:111]
	v_mfma_f32_16x16x32_bf16 v[104:107], v[224:227], v[28:31], v[104:107]
	ds_read_b128 v[224:227], v151 offset:6784
	s_waitcnt lgkmcnt(5)
	v_mfma_f32_16x16x32_bf16 v[112:115], v[228:231], v[8:11], v[96:99]
	v_mfma_f32_16x16x32_bf16 v[108:111], v[228:231], v[20:23], v[100:103]
	ds_read_b128 v[228:231], v151 offset:9984
	s_waitcnt lgkmcnt(5)
	v_mfma_f32_16x16x32_bf16 v[112:115], v[248:251], v[12:15], v[112:115]
	v_mfma_f32_16x16x32_bf16 v[108:111], v[248:251], v[24:27], v[108:111]
	ds_read_b128 v[248:251], v151 offset:10048
	s_waitcnt lgkmcnt(5)
	v_mfma_f32_16x16x32_bf16 v[124:127], v[252:255], v[16:19], v[112:115]
	v_mfma_f32_16x16x32_bf16 v[108:111], v[252:255], v[28:31], v[108:111]
	ds_read_b128 v[252:255], v151 offset:10112
	s_waitcnt lgkmcnt(5)
	v_mfma_f32_16x16x32_bf16 v[120:123], v[216:219], v[8:11], v[96:99]
	v_mfma_f32_16x16x32_bf16 v[112:115], v[216:219], v[20:23], v[100:103]
	s_waitcnt lgkmcnt(4)
	v_mfma_f32_16x16x32_bf16 v[120:123], v[220:223], v[12:15], v[120:123]
	v_mfma_f32_16x16x32_bf16 v[112:115], v[220:223], v[24:27], v[112:115]
	s_waitcnt lgkmcnt(3)
	v_mfma_f32_16x16x32_bf16 v[128:131], v[224:227], v[16:19], v[120:123]
	v_mfma_f32_16x16x32_bf16 v[112:115], v[224:227], v[28:31], v[112:115]
	s_waitcnt lgkmcnt(2)
	v_mfma_f32_16x16x32_bf16 v[132:135], v[228:231], v[8:11], v[96:99]
	v_mfma_f32_16x16x32_bf16 v[120:123], v[228:231], v[20:23], v[100:103]
	s_waitcnt lgkmcnt(1)
	v_mfma_f32_16x16x32_bf16 v[132:135], v[248:251], v[12:15], v[132:135]
	v_mfma_f32_16x16x32_bf16 v[120:123], v[248:251], v[24:27], v[120:123]
	s_waitcnt lgkmcnt(0)
	v_mfma_f32_16x16x32_bf16 v[132:135], v[252:255], v[16:19], v[132:135]
	v_mfma_f32_16x16x32_bf16 v[120:123], v[252:255], v[28:31], v[120:123]
	s_setprio 0
	v_max_f32_e32 v97, v117, v117
	v_max_f32_e32 v98, v116, v116
	v_max_f32_e32 v97, v98, v97
	v_max_f32_e32 v98, v119, v119
	v_max_f32_e32 v99, v118, v118
	v_max_f32_e32 v98, v99, v98
	v_max_f32_e32 v99, v127, v127
	v_max_f32_e32 v101, v126, v126
	v_max_f32_e32 v99, v101, v99
	v_max3_f32 v99, v124, v125, v99
	v_max3_f32 v97, v97, v98, v99
	v_max_f32_e32 v98, v131, v131
	v_max_f32_e32 v99, v130, v130
	v_max_f32_e32 v98, v99, v98
	v_max_f32_e32 v99, v135, v135
	v_max_f32_e32 v101, v134, v134
	v_max_f32_e32 v99, v101, v99
	v_max3_f32 v98, v128, v129, v98
	v_max3_f32 v99, v132, v133, v99
	v_max3_f32 v97, v97, v98, v99
	v_mov_b32_e32 v98, v97
	v_max_f32_e32 v99, v104, v104
	v_max_f32_e32 v101, v106, v106
	v_max_f32_e32 v102, v110, v110
	s_mov_b32 s6, 0x41000000
	s_nop 1
	v_permlane16_swap_b32_e32 v98, v97
	v_max_f32_e32 v97, v97, v98
	v_mov_b32_e32 v98, v97
	s_nop 1
	v_permlane32_swap_b32_e32 v98, v97
	v_max_f32_e32 v97, v97, v98
	v_max_f32_e32 v98, v105, v105
	v_max_f32_e32 v98, v99, v98
	v_max_f32_e32 v99, v107, v107
	v_max_f32_e32 v99, v101, v99
	v_max_f32_e32 v101, v111, v111
	v_max_f32_e32 v101, v102, v101
	v_max3_f32 v101, v108, v109, v101
	v_max3_f32 v98, v98, v99, v101
	v_max_f32_e32 v99, v115, v115
	v_max_f32_e32 v101, v114, v114
	v_max_f32_e32 v99, v101, v99
	v_max_f32_e32 v101, v123, v123
	v_max_f32_e32 v102, v122, v122
	v_max_f32_e32 v101, v102, v101
	v_max3_f32 v99, v112, v113, v99
	v_max3_f32 v101, v120, v121, v101
	v_max3_f32 v98, v98, v99, v101
	v_mov_b32_e32 v99, v98
	s_nop 1
	v_permlane16_swap_b32_e32 v99, v98
	v_max_f32_e32 v98, v98, v99
	v_mov_b32_e32 v99, v98
	s_nop 1
	v_permlane32_swap_b32_e32 v99, v98
	v_max_f32_e32 v98, v98, v99
	v_max_f32_e32 v99, v97, v98
	v_cmp_lt_f32_e32 vcc, s6, v99
	s_cbranch_vccz .LBB0_293
	v_max_f32_e32 v96, v97, v97
	v_max_f32_e32 v96, 0, v96
	v_pk_add_f32 v[116:117], v[116:117], v[96:97] op_sel_hi:[1,0] neg_lo:[0,1] neg_hi:[0,1]
	v_pk_add_f32 v[118:119], v[118:119], v[96:97] op_sel_hi:[1,0] neg_lo:[0,1] neg_hi:[0,1]
	v_pk_add_f32 v[124:125], v[124:125], v[96:97] op_sel_hi:[1,0] neg_lo:[0,1] neg_hi:[0,1]
	v_pk_add_f32 v[126:127], v[126:127], v[96:97] op_sel_hi:[1,0] neg_lo:[0,1] neg_hi:[0,1]
	v_pk_add_f32 v[128:129], v[128:129], v[96:97] op_sel_hi:[1,0] neg_lo:[0,1] neg_hi:[0,1]
	v_pk_add_f32 v[130:131], v[130:131], v[96:97] op_sel_hi:[1,0] neg_lo:[0,1] neg_hi:[0,1]
	v_pk_add_f32 v[132:133], v[132:133], v[96:97] op_sel_hi:[1,0] neg_lo:[0,1] neg_hi:[0,1]
	v_pk_add_f32 v[134:135], v[134:135], v[96:97] op_sel_hi:[1,0] neg_lo:[0,1] neg_hi:[0,1]
	v_max_f32_e32 v97, v98, v98
	v_exp_f32_e64 v100, -v96
	v_max_f32_e32 v98, 0, v97
	v_exp_f32_e64 v102, -v98
	v_mov_b32_e32 v99, v96
	v_pk_add_f32 v[164:165], v[164:165], v[98:99]
	v_mov_b32_e32 v103, v100
	v_pk_mul_f32 v[94:95], v[94:95], v[100:101] op_sel_hi:[1,0]
	v_pk_mul_f32 v[92:93], v[92:93], v[100:101] op_sel_hi:[1,0]
	v_pk_mul_f32 v[90:91], v[90:91], v[100:101] op_sel_hi:[1,0]
	v_pk_mul_f32 v[88:89], v[88:89], v[100:101] op_sel_hi:[1,0]
	v_pk_mul_f32 v[86:87], v[86:87], v[100:101] op_sel_hi:[1,0]
	v_pk_mul_f32 v[84:85], v[84:85], v[100:101] op_sel_hi:[1,0]
	v_pk_mul_f32 v[82:83], v[82:83], v[100:101] op_sel_hi:[1,0]
	v_pk_mul_f32 v[80:81], v[80:81], v[100:101] op_sel_hi:[1,0]
	v_pk_mul_f32 v[166:167], v[166:167], v[102:103]
	v_pk_mul_f32 v[78:79], v[78:79], v[102:103] op_sel_hi:[1,0]
	v_pk_mul_f32 v[76:77], v[76:77], v[102:103] op_sel_hi:[1,0]
	v_pk_mul_f32 v[74:75], v[74:75], v[102:103] op_sel_hi:[1,0]
	v_pk_mul_f32 v[72:73], v[72:73], v[102:103] op_sel_hi:[1,0]
	v_pk_mul_f32 v[70:71], v[70:71], v[102:103] op_sel_hi:[1,0]
	v_pk_mul_f32 v[68:69], v[68:69], v[102:103] op_sel_hi:[1,0]
	v_pk_mul_f32 v[66:67], v[66:67], v[102:103] op_sel_hi:[1,0]
	v_pk_mul_f32 v[64:65], v[64:65], v[102:103] op_sel_hi:[1,0]
	v_pk_add_f32 v[104:105], v[104:105], v[98:99] op_sel_hi:[1,0] neg_lo:[0,1] neg_hi:[0,1]
	v_pk_add_f32 v[106:107], v[106:107], v[98:99] op_sel_hi:[1,0] neg_lo:[0,1] neg_hi:[0,1]
	v_pk_add_f32 v[108:109], v[108:109], v[98:99] op_sel_hi:[1,0] neg_lo:[0,1] neg_hi:[0,1]
	v_pk_add_f32 v[110:111], v[110:111], v[98:99] op_sel_hi:[1,0] neg_lo:[0,1] neg_hi:[0,1]
	v_pk_add_f32 v[112:113], v[112:113], v[98:99] op_sel_hi:[1,0] neg_lo:[0,1] neg_hi:[0,1]
	v_pk_add_f32 v[114:115], v[114:115], v[98:99] op_sel_hi:[1,0] neg_lo:[0,1] neg_hi:[0,1]
	v_pk_add_f32 v[120:121], v[120:121], v[98:99] op_sel_hi:[1,0] neg_lo:[0,1] neg_hi:[0,1]
	v_pk_add_f32 v[122:123], v[122:123], v[98:99] op_sel_hi:[1,0] neg_lo:[0,1] neg_hi:[0,1]
	v_xor_b32_e32 v96, 0x80000000, v165
	v_pk_add_f32 v[100:101], v[164:165], 0 neg_lo:[1,1] neg_hi:[1,1]
.LBB0_293:
	ds_read_b128 v[248:251], v136 offset:13312
	ds_read_b128 v[252:255], v136 offset:13376
	v_exp_f32_e32 v217, v116
	v_exp_f32_e32 v216, v104
	v_exp_f32_e32 v219, v117
	v_exp_f32_e32 v218, v105
	v_exp_f32_e32 v221, v118
	v_exp_f32_e32 v220, v106
	v_exp_f32_e32 v223, v119
	v_exp_f32_e32 v222, v107
	v_exp_f32_e32 v225, v124
	v_exp_f32_e32 v224, v108
	v_pk_add_f32 v[104:105], v[216:217], 0 op_sel_hi:[1,0]
	v_exp_f32_e32 v227, v125
	v_exp_f32_e32 v226, v109
	v_pk_add_f32 v[104:105], v[218:219], v[104:105]
	v_exp_f32_e32 v229, v126
	v_pk_add_f32 v[104:105], v[220:221], v[104:105]
	v_exp_f32_e32 v228, v110
	v_exp_f32_e32 v231, v127
	v_pk_add_f32 v[104:105], v[222:223], v[104:105]
	v_exp_f32_e32 v230, v111
	v_exp_f32_e32 v233, v128
	v_pk_add_f32 v[104:105], v[224:225], v[104:105]
	v_exp_f32_e32 v232, v112
	v_exp_f32_e32 v235, v129
	v_pk_add_f32 v[104:105], v[226:227], v[104:105]
	v_exp_f32_e32 v234, v113
	v_exp_f32_e32 v237, v130
	v_exp_f32_e32 v236, v114
	v_pk_add_f32 v[104:105], v[228:229], v[104:105]
	v_exp_f32_e32 v131, v131
	v_exp_f32_e32 v130, v115
	v_pk_add_f32 v[104:105], v[230:231], v[104:105]
	v_exp_f32_e32 v239, v132
	v_exp_f32_e32 v238, v120
	v_pk_add_f32 v[104:105], v[232:233], v[104:105]
	v_exp_f32_e32 v133, v133
	v_exp_f32_e32 v132, v121
	v_pk_add_f32 v[104:105], v[234:235], v[104:105]
	v_exp_f32_e32 v241, v134
	v_exp_f32_e32 v240, v122
	v_pk_add_f32 v[104:105], v[236:237], v[104:105]
	v_exp_f32_e32 v135, v135
	v_exp_f32_e32 v134, v123
	v_pk_add_f32 v[104:105], v[130:131], v[104:105]
	v_mov_b32_e32 v101, v100
	v_pk_add_f32 v[104:105], v[238:239], v[104:105]
	v_mov_b32_e32 v102, v100
	v_pk_add_f32 v[104:105], v[132:133], v[104:105]
	v_mov_b32_e32 v103, v100
	v_pk_add_f32 v[104:105], v[240:241], v[104:105]
	v_mov_b32_e32 v97, v96
	v_pk_add_f32 v[104:105], v[134:135], v[104:105]
	v_mov_b32_e32 v98, v96
	v_mov_b32_e32 v99, v96
	v_cvt_pk_bf16_f32 v116, v217, v219
	v_cvt_pk_bf16_f32 v117, v221, v223
	v_cvt_pk_bf16_f32 v118, v225, v227
	v_cvt_pk_bf16_f32 v119, v229, v231
	v_cvt_pk_bf16_f32 v124, v233, v235
	v_cvt_pk_bf16_f32 v125, v237, v131
	v_cvt_pk_bf16_f32 v126, v239, v133
	v_cvt_pk_bf16_f32 v127, v241, v135
	v_pk_add_f32 v[128:129], v[104:105], v[166:167]
	v_cvt_pk_bf16_f32 v104, v216, v218
	v_cvt_pk_bf16_f32 v105, v220, v222
	v_cvt_pk_bf16_f32 v106, v224, v226
	v_cvt_pk_bf16_f32 v107, v228, v230
	v_cvt_pk_bf16_f32 v108, v232, v234
	v_cvt_pk_bf16_f32 v109, v236, v130
	v_cvt_pk_bf16_f32 v110, v238, v132
	v_cvt_pk_bf16_f32 v111, v240, v134
	s_setprio 1
	ds_read_b128 v[216:219], v136 offset:15616
	ds_read_b128 v[220:223], v136 offset:15680
	ds_read_b128 v[224:227], v136 offset:17920
	ds_read_b128 v[228:231], v136 offset:17984
	ds_read_b128 v[232:235], v136 offset:20224
	ds_read_b128 v[236:239], v136 offset:20288
	s_waitcnt lgkmcnt(6)
	v_mfma_f32_16x16x32_bf16 v[92:95], v[248:251], v[116:119], v[92:95]
	v_mfma_f32_16x16x32_bf16 v[112:115], v[248:251], v[104:107], v[76:79]
	s_waitcnt lgkmcnt(6)
	v_mfma_f32_16x16x32_bf16 v[76:79], v[252:255], v[124:127], v[92:95]
	v_mfma_f32_16x16x32_bf16 v[92:95], v[252:255], v[108:111], v[112:115]
	s_waitcnt lgkmcnt(5)
	v_mfma_f32_16x16x32_bf16 v[88:91], v[216:219], v[116:119], v[88:91]
	v_mfma_f32_16x16x32_bf16 v[72:75], v[216:219], v[104:107], v[72:75]
	s_waitcnt lgkmcnt(4)
	v_mfma_f32_16x16x32_bf16 v[88:91], v[220:223], v[124:127], v[88:91]
	v_mfma_f32_16x16x32_bf16 v[72:75], v[220:223], v[108:111], v[72:75]
	s_waitcnt lgkmcnt(3)
	v_mfma_f32_16x16x32_bf16 v[84:87], v[224:227], v[116:119], v[84:87]
	v_mfma_f32_16x16x32_bf16 v[68:71], v[224:227], v[104:107], v[68:71]
	s_waitcnt lgkmcnt(2)
	v_mfma_f32_16x16x32_bf16 v[84:87], v[228:231], v[124:127], v[84:87]
	v_mfma_f32_16x16x32_bf16 v[68:71], v[228:231], v[108:111], v[68:71]
	s_waitcnt lgkmcnt(1)
	v_mfma_f32_16x16x32_bf16 v[64:67], v[232:235], v[104:107], v[64:67]
	v_mfma_f32_16x16x32_bf16 v[80:83], v[232:235], v[116:119], v[80:83]
	s_waitcnt lgkmcnt(0)
	v_mfma_f32_16x16x32_bf16 v[80:83], v[236:239], v[124:127], v[80:83]
	v_mfma_f32_16x16x32_bf16 v[64:67], v[236:239], v[108:111], v[64:67]
	s_setprio 0
	s_min_i32 s6, s1, s4
	s_lshl_b32 s7, s6, 6
	s_add_i32 s7, s7, s16
	s_waitcnt vmcnt(8)
	ds_write_b128 v208, v[0:3] offset:22528
	s_waitcnt vmcnt(7)
	ds_write_b128 v209, v[4:7] offset:22528
	s_waitcnt vmcnt(7)
	ds_write_b128 v210, v[36:39] offset:22528
	s_waitcnt vmcnt(6)
	ds_write_b64 v211, v[40:41] offset:35840
	ds_write_b64 v212, v[42:43] offset:35840
	s_waitcnt vmcnt(5)
	ds_write_b64 v213, v[32:33] offset:35840
	ds_write_b64 v214, v[34:35] offset:35840
	v_add_u32_e32 v32, s7, v205
	v_add_u32_e32 v0, s7, v203
	v_add_u32_e32 v4, s7, v204
	v_ashrrev_i32_e32 v33, 31, v32
	v_ashrrev_i32_e32 v1, 31, v0
	v_ashrrev_i32_e32 v5, 31, v4
	v_lshlrev_b64 v[34:35], 9, v[32:33]
	v_lshlrev_b64 v[32:33], 6, v[32:33]
	v_lshlrev_b64 v[2:3], 9, v[0:1]
	v_lshlrev_b64 v[0:1], 6, v[0:1]
	v_lshlrev_b64 v[6:7], 9, v[4:5]
	v_lshlrev_b64 v[4:5], 6, v[4:5]
	v_lshl_add_u64 v[32:33], v[160:161], 0, v[32:33]
	v_lshl_add_u64 v[0:1], v[152:153], 0, v[0:1]
	v_lshl_add_u64 v[4:5], v[156:157], 0, v[4:5]
	v_lshl_add_u64 v[34:35], v[162:163], 0, v[34:35]
	v_lshl_add_u64 v[32:33], v[32:33], 0, s[18:19]
	v_lshl_add_u64 v[2:3], v[154:155], 0, v[2:3]
	v_lshl_add_u64 v[0:1], v[0:1], 0, s[18:19]
	v_lshl_add_u64 v[6:7], v[158:159], 0, v[6:7]
	v_lshl_add_u64 v[4:5], v[4:5], 0, s[18:19]
	v_cndmask_b32_e64 v33, v33, v35, s[42:43]
	v_cndmask_b32_e64 v32, v32, v34, s[42:43]
	s_lshl_b32 s94, s6, 7
	s_waitcnt lgkmcnt(0)
	s_barrier
	v_cndmask_b32_e64 v1, v1, v3, s[38:39]
	v_cndmask_b32_e64 v0, v0, v2, s[38:39]
	v_cndmask_b32_e64 v5, v5, v7, s[40:41]
	v_cndmask_b32_e64 v4, v4, v6, s[40:41]
	global_load_dwordx4 v[36:39], v[32:33], off
	v_lshl_add_u64 v[32:33], v[146:147], 0, s[94:95]
	v_lshl_add_u64 v[34:35], v[148:149], 0, s[94:95]
	global_load_dwordx4 v[0:3], v[0:1], off
	s_nop 0
	global_load_dwordx4 v[4:7], v[4:5], off
	s_nop 0
	global_load_dwordx4 v[40:43], v[32:33], off
	s_nop 0
	global_load_dwordx4 v[32:35], v[34:35], off
	s_setprio 1
	ds_read_b128 v[216:219], v151 offset:22528
	ds_read_b128 v[220:223], v151 offset:22592
	ds_read_b128 v[224:227], v151 offset:22656
	ds_read_b128 v[228:231], v151 offset:25856
	ds_read_b128 v[248:251], v151 offset:25920
	ds_read_b128 v[252:255], v151 offset:25984
	s_waitcnt lgkmcnt(5)
	v_mfma_f32_16x16x32_bf16 v[108:111], v[216:219], v[8:11], v[96:99]
	v_mfma_f32_16x16x32_bf16 v[104:107], v[216:219], v[20:23], v[100:103]
	ds_read_b128 v[216:219], v151 offset:29184
	s_waitcnt lgkmcnt(5)
	v_mfma_f32_16x16x32_bf16 v[108:111], v[220:223], v[12:15], v[108:111]
	v_mfma_f32_16x16x32_bf16 v[104:107], v[220:223], v[24:27], v[104:107]
	ds_read_b128 v[220:223], v151 offset:29248
	s_waitcnt lgkmcnt(5)
	v_mfma_f32_16x16x32_bf16 v[116:119], v[224:227], v[16:19], v[108:111]
	v_mfma_f32_16x16x32_bf16 v[104:107], v[224:227], v[28:31], v[104:107]
	ds_read_b128 v[224:227], v151 offset:29312
	s_waitcnt lgkmcnt(5)
	v_mfma_f32_16x16x32_bf16 v[112:115], v[228:231], v[8:11], v[96:99]
	v_mfma_f32_16x16x32_bf16 v[108:111], v[228:231], v[20:23], v[100:103]
	ds_read_b128 v[228:231], v151 offset:32512
	s_waitcnt lgkmcnt(5)
	v_mfma_f32_16x16x32_bf16 v[112:115], v[248:251], v[12:15], v[112:115]
	v_mfma_f32_16x16x32_bf16 v[108:111], v[248:251], v[24:27], v[108:111]
	ds_read_b128 v[248:251], v151 offset:32576
	s_waitcnt lgkmcnt(5)
	v_mfma_f32_16x16x32_bf16 v[120:123], v[252:255], v[16:19], v[112:115]
	v_mfma_f32_16x16x32_bf16 v[112:115], v[252:255], v[28:31], v[108:111]
	ds_read_b128 v[252:255], v151 offset:32640
	s_waitcnt lgkmcnt(5)
	v_mfma_f32_16x16x32_bf16 v[124:127], v[216:219], v[8:11], v[96:99]
	v_mfma_f32_16x16x32_bf16 v[108:111], v[216:219], v[20:23], v[100:103]
	s_waitcnt lgkmcnt(4)
	v_mfma_f32_16x16x32_bf16 v[124:127], v[220:223], v[12:15], v[124:127]
	v_mfma_f32_16x16x32_bf16 v[108:111], v[220:223], v[24:27], v[108:111]
	s_waitcnt lgkmcnt(3)
	v_mfma_f32_16x16x32_bf16 v[124:127], v[224:227], v[16:19], v[124:127]
	v_mfma_f32_16x16x32_bf16 v[108:111], v[224:227], v[28:31], v[108:111]
	s_waitcnt lgkmcnt(2)
	v_mfma_f32_16x16x32_bf16 v[96:99], v[228:231], v[8:11], v[96:99]
	v_mfma_f32_16x16x32_bf16 v[100:103], v[228:231], v[20:23], v[100:103]
	s_waitcnt lgkmcnt(1)
	v_mfma_f32_16x16x32_bf16 v[96:99], v[248:251], v[12:15], v[96:99]
	v_mfma_f32_16x16x32_bf16 v[130:133], v[248:251], v[24:27], v[100:103]
	s_waitcnt lgkmcnt(0)
	v_mfma_f32_16x16x32_bf16 v[100:103], v[252:255], v[16:19], v[96:99]
	v_mfma_f32_16x16x32_bf16 v[96:99], v[252:255], v[28:31], v[130:133]
	s_setprio 0
	s_nop 4
	v_max_f32_e32 v130, v117, v117
	v_max_f32_e32 v131, v116, v116
	v_max_f32_e32 v130, v131, v130
	v_max_f32_e32 v131, v119, v119
	v_max_f32_e32 v132, v118, v118
	v_max_f32_e32 v131, v132, v131
	v_max_f32_e32 v132, v123, v123
	v_max_f32_e32 v133, v122, v122
	v_max_f32_e32 v132, v133, v132
	v_max3_f32 v132, v120, v121, v132
	v_max3_f32 v130, v130, v131, v132
	v_max_f32_e32 v131, v127, v127
	v_max_f32_e32 v132, v126, v126
	v_max_f32_e32 v131, v132, v131
	v_max_f32_e32 v132, v103, v103
	v_max_f32_e32 v133, v102, v102
	v_max_f32_e32 v132, v133, v132
	v_max3_f32 v131, v124, v125, v131
	v_max3_f32 v132, v100, v101, v132
	v_max3_f32 v130, v130, v131, v132
	v_mov_b32_e32 v131, v130
	v_max_f32_e32 v132, v104, v104
	v_max_f32_e32 v133, v106, v106
	v_max_f32_e32 v134, v114, v114
	s_mov_b32 s6, 0x41000000
	s_nop 1
	v_permlane16_swap_b32_e32 v131, v130
	v_max_f32_e32 v130, v130, v131
	v_mov_b32_e32 v131, v130
	s_nop 1
	v_permlane32_swap_b32_e32 v131, v130
	v_max_f32_e32 v130, v130, v131
	v_max_f32_e32 v131, v105, v105
	v_max_f32_e32 v131, v132, v131
	v_max_f32_e32 v132, v107, v107
	v_max_f32_e32 v132, v133, v132
	v_max_f32_e32 v133, v115, v115
	v_max_f32_e32 v133, v134, v133
	v_max3_f32 v133, v112, v113, v133
	v_max3_f32 v131, v131, v132, v133
	v_max_f32_e32 v132, v111, v111
	v_max_f32_e32 v133, v110, v110
	v_max_f32_e32 v132, v133, v132
	v_max_f32_e32 v133, v99, v99
	v_max_f32_e32 v134, v98, v98
	v_max_f32_e32 v133, v134, v133
	v_max3_f32 v132, v108, v109, v132
	v_max3_f32 v133, v96, v97, v133
	v_max3_f32 v131, v131, v132, v133
	v_mov_b32_e32 v132, v131
	s_nop 1
	v_permlane16_swap_b32_e32 v132, v131
	v_max_f32_e32 v131, v131, v132
	v_mov_b32_e32 v132, v131
	s_nop 1
	v_permlane32_swap_b32_e32 v132, v131
	v_max_f32_e32 v131, v131, v132
	v_max_f32_e32 v132, v130, v131
	v_cmp_lt_f32_e32 vcc, s6, v132
	s_cbranch_vccz .LBB0_290
	v_max_f32_e32 v130, v130, v130
	v_max_f32_e32 v130, 0, v130
	v_pk_add_f32 v[116:117], v[116:117], v[130:131] op_sel_hi:[1,0] neg_lo:[0,1] neg_hi:[0,1]
	v_pk_add_f32 v[118:119], v[118:119], v[130:131] op_sel_hi:[1,0] neg_lo:[0,1] neg_hi:[0,1]
	v_pk_add_f32 v[120:121], v[120:121], v[130:131] op_sel_hi:[1,0] neg_lo:[0,1] neg_hi:[0,1]
	v_pk_add_f32 v[122:123], v[122:123], v[130:131] op_sel_hi:[1,0] neg_lo:[0,1] neg_hi:[0,1]
	v_pk_add_f32 v[124:125], v[124:125], v[130:131] op_sel_hi:[1,0] neg_lo:[0,1] neg_hi:[0,1]
	v_pk_add_f32 v[126:127], v[126:127], v[130:131] op_sel_hi:[1,0] neg_lo:[0,1] neg_hi:[0,1]
	v_pk_add_f32 v[100:101], v[100:101], v[130:131] op_sel_hi:[1,0] neg_lo:[0,1] neg_hi:[0,1]
	v_pk_add_f32 v[102:103], v[102:103], v[130:131] op_sel_hi:[1,0] neg_lo:[0,1] neg_hi:[0,1]
	v_max_f32_e32 v131, v131, v131
	v_exp_f32_e64 v132, -v130
	v_max_f32_e32 v134, 0, v131
	v_exp_f32_e64 v166, -v134
	v_mov_b32_e32 v135, v130
	v_mov_b32_e32 v167, v132
	v_pk_mul_f32 v[78:79], v[78:79], v[132:133] op_sel_hi:[1,0]
	v_pk_mul_f32 v[76:77], v[76:77], v[132:133] op_sel_hi:[1,0]
	v_pk_mul_f32 v[90:91], v[90:91], v[132:133] op_sel_hi:[1,0]
	v_pk_mul_f32 v[88:89], v[88:89], v[132:133] op_sel_hi:[1,0]
	v_pk_mul_f32 v[86:87], v[86:87], v[132:133] op_sel_hi:[1,0]
	v_pk_mul_f32 v[84:85], v[84:85], v[132:133] op_sel_hi:[1,0]
	v_pk_mul_f32 v[82:83], v[82:83], v[132:133] op_sel_hi:[1,0]
	v_pk_mul_f32 v[80:81], v[80:81], v[132:133] op_sel_hi:[1,0]
	v_pk_add_f32 v[164:165], v[164:165], v[134:135]
	v_pk_mul_f32 v[128:129], v[128:129], v[166:167]
	v_pk_mul_f32 v[94:95], v[94:95], v[166:167] op_sel_hi:[1,0]
	v_pk_mul_f32 v[92:93], v[92:93], v[166:167] op_sel_hi:[1,0]
	v_pk_mul_f32 v[74:75], v[74:75], v[166:167] op_sel_hi:[1,0]
	v_pk_mul_f32 v[72:73], v[72:73], v[166:167] op_sel_hi:[1,0]
	v_pk_mul_f32 v[70:71], v[70:71], v[166:167] op_sel_hi:[1,0]
	v_pk_mul_f32 v[68:69], v[68:69], v[166:167] op_sel_hi:[1,0]
	v_pk_mul_f32 v[66:67], v[66:67], v[166:167] op_sel_hi:[1,0]
	v_pk_mul_f32 v[64:65], v[64:65], v[166:167] op_sel_hi:[1,0]
	v_pk_add_f32 v[104:105], v[104:105], v[134:135] op_sel_hi:[1,0] neg_lo:[0,1] neg_hi:[0,1]
	v_pk_add_f32 v[106:107], v[106:107], v[134:135] op_sel_hi:[1,0] neg_lo:[0,1] neg_hi:[0,1]
	v_pk_add_f32 v[112:113], v[112:113], v[134:135] op_sel_hi:[1,0] neg_lo:[0,1] neg_hi:[0,1]
	v_pk_add_f32 v[114:115], v[114:115], v[134:135] op_sel_hi:[1,0] neg_lo:[0,1] neg_hi:[0,1]
	v_pk_add_f32 v[108:109], v[108:109], v[134:135] op_sel_hi:[1,0] neg_lo:[0,1] neg_hi:[0,1]
	v_pk_add_f32 v[110:111], v[110:111], v[134:135] op_sel_hi:[1,0] neg_lo:[0,1] neg_hi:[0,1]
	v_pk_add_f32 v[96:97], v[96:97], v[134:135] op_sel_hi:[1,0] neg_lo:[0,1] neg_hi:[0,1]
	v_pk_add_f32 v[98:99], v[98:99], v[134:135] op_sel_hi:[1,0] neg_lo:[0,1] neg_hi:[0,1]
	s_branch .LBB0_290
